# hgrn output units: one acquire over all 8 chain flags at the first unit (single L1 invalidate), later units keep their operand prefetch
# speedup vs baseline: 1.0207x; 1.0033x over previous
.LBB0_702:
	s_add_i32 s10, s63, 0xffffffb8
	s_ashr_i32 s63, s10, 5
	s_lshl_b32 s26, 1, s63
	s_and_b32 s6, s26, s70
	s_cmp_lg_u32 s6, 0
	s_cbranch_scc1 .LBB0_714
	s_and_b64 vcc, exec, s[4:5]
	s_cbranch_vccnz .LBB0_713
	s_mov_b64 s[6:7], s[0:1]
	s_load_dwordx2 s[6:7], s[6:7], 0xa8
	s_lshl_b32 s8, s51, 2
	s_waitcnt lgkmcnt(0)
	s_add_u32 s6, s6, s8
	s_addc_u32 s7, s7, 0
	s_add_u32 s6, s6, 0x20000
	s_addc_u32 s7, s7, 0
	s_mov_b32 s27, 0x3fffff
.Lacq_poll:
	global_load_dword v0, v201, s[6:7] sc1
	global_load_dword v1, v201, s[6:7] offset:256 sc1
	global_load_dword v2, v201, s[6:7] offset:512 sc1
	global_load_dword v3, v201, s[6:7] offset:768 sc1
	global_load_dword v4, v201, s[6:7] offset:1024 sc1
	global_load_dword v5, v201, s[6:7] offset:1280 sc1
	global_load_dword v6, v201, s[6:7] offset:1536 sc1
	global_load_dword v7, v201, s[6:7] offset:1792 sc1
	s_waitcnt vmcnt(0)
	v_and_b32_e32 v0, v0, v1
	v_and_b32_e32 v2, v2, v3
	v_and_b32_e32 v4, v4, v5
	v_and_b32_e32 v6, v6, v7
	v_and_b32_e32 v0, v0, v2
	v_and_b32_e32 v4, v4, v6
	v_and_b32_e32 v0, v0, v4
	v_cmp_ne_u32_e32 vcc, 0, v0
	s_cbranch_vccnz .Lacq_done
	s_sleep 8
	s_add_i32 s27, s27, -1
	s_cmp_lg_u32 s27, 0
	s_cbranch_scc1 .Lacq_poll

.LBB0_713:
	s_or_b32 s70, s70, 15
	s_barrier
